# DA loop: K and V MFMA fragments share one pool of 8 buffers, every fragment fetched from LDS 8 MFMAs ahead (V was 4, K was 12); on top of v135
# baseline (speedup 1.0000x reference)
; __device__ void da_unit(char* lds, const Params& p, int layer, int unit) {
;     ...
;         char* nK = lds + ((it + 1) & 1) * DA_STAGE;
;         const int tn = tile_of(it + 1 < NT ? it + 1 : it);
;         if (it + 1 < NT) {
; #pragma unroll
;             for (int j = 0; j < 4; ++j) rk[j] = *(const u32x4*)(Kg + (size_t)tn * 16384 + j * 4096);
;         }
.Lda_p_noflip:
	s_add_i32 s1, s8, 0x11800
	v_add3_u32 v234, s1, v186, v152
	s_mov_b32 s2, 0x8800
	v_add3_u32 v178, s2, v152, v154
	ds_read_b128 v[210:213], v234 offset:0
	ds_read_b128 v[214:217], v234 offset:32
	ds_read_b128 v[218:221], v234 offset:64
	ds_read_b128 v[222:225], v234 offset:96
	ds_read_b128 v[226:229], v178 offset:27712
	ds_read_b128 v[230:233], v178 offset:32320
	ds_read_b128 v[174:177], v234 offset:8768
	ds_read_b128 v[246:249], v178 offset:18528
	s_add_i32 s0, s14, 2
	s_cmp_lt_u32 2, s9
	s_cselect_b32 s0, s0, 13
	s_lshl_b32 s18, s0, 15
	s_mov_b32 s19, 0
	v_lshl_add_u64 v[156:157], v[148:149], 0, s[18:19]
	global_load_dwordx4 v[130:133], v[156:157], off
	s_add_u32 s18, s18, 0x2000
	v_lshl_add_u64 v[156:157], v[148:149], 0, s[18:19]
	global_load_dwordx4 v[134:137], v[156:157], off
	s_add_u32 s18, s18, 0x2000
	v_lshl_add_u64 v[156:157], v[148:149], 0, s[18:19]
	global_load_dwordx4 v[138:141], v[156:157], off
	s_add_u32 s18, s18, 0x2000
	v_lshl_add_u64 v[156:157], v[148:149], 0, s[18:19]
	global_load_dwordx4 v[142:145], v[156:157], off
	s_waitcnt lgkmcnt(7)
	v_mfma_f32_32x32x16_bf16 v[82:97], v[210:213], v[114:117], v[66:81]
	ds_read_b128 v[210:213], v234 offset:8704
	s_waitcnt lgkmcnt(7)
	v_mfma_f32_32x32x16_bf16 v[82:97], v[214:217], v[118:121], v[82:97]
	ds_read_b128 v[214:217], v178 offset:18496
	s_waitcnt lgkmcnt(7)
	v_mfma_f32_32x32x16_bf16 v[82:97], v[218:221], v[122:125], v[82:97]
	ds_read_b128 v[218:221], v178 offset:23104
	s_waitcnt lgkmcnt(7)
	v_mfma_f32_32x32x16_bf16 v[82:97], v[222:225], v[126:129], v[82:97]
	ds_read_b128 v[222:225], v234 offset:8736
	s_mov_b32 s4, 1
	s_waitcnt lgkmcnt(0)

; __device__ void da_unit(char* lds, const Params& p, int layer, int unit) {
;     ...
;     for (int it = 1; it < NT - qb; ++it) {
;         const int kt = tile_of(it);
;         const char* cK = lds + (it & 1) * DA_STAGE;
;         const char* cV = cK + DA_KBYTES;
;         char* nK = lds + ((it + 1) & 1) * DA_STAGE;
;         const int tn = tile_of(it + 1 < NT ? it + 1 : it);
;         if (it + 1 < NT) {
; #pragma unroll
;             for (int j = 0; j < 4; ++j) rk[j] = *(const u32x4*)(Kg + (size_t)tn * 16384 + j * 4096);
;         }
;     ...
;         DA_FAST_HALF(Bs, -slope2, 0)
;         if (it + 1 < NT) {
; #pragma unroll
;             for (int j = 0; j < 4; ++j) *(u32x4*)(nK + (kr_ + 32 * j) * DA_KP + kc_ * 16) = rk[j];
; #pragma unroll
;             for (int j = 0; j < 4; ++j) rk[j] = *(const u32x4*)(Vg + (size_t)tn * 16384 + j * 4096);
;         }
.Lda_noflip:
	s_add_i32 s0, s14, s4
	s_sub_i32 s1, 15, s4
	s_cmp_lt_u32 s4, s9
	s_cselect_b32 s10, s0, s1
	s_lshl_b32 s11, s10, 7
	s_add_i32 s16, s4, 1
	s_add_i32 s0, s14, s16
	s_sub_i32 s1, 15, s16
	s_cmp_lt_u32 s16, s9
	s_cselect_b32 s0, s0, s1
	s_max_i32 s0, s0, 0
	s_add_i32 s16, s4, 2
	s_add_i32 s3, s14, s16
	s_sub_i32 s1, 15, s16
	s_cmp_lt_u32 s16, s9
	s_cselect_b32 s3, s3, s1
	s_bitcmp1_b32 s4, 0
	s_cselect_b32 s17, 0x11800, 0
	s_sub_i32 s5, 0x11800, s17
	s_add_i32 s1, s17, s8
	s_add_i32 s2, s17, 0x8800
	v_add3_u32 v234, s1, v186, v152
	v_add3_u32 v235, s2, v152, v154
	s_add_i32 s1, s5, s8
	s_add_i32 s2, s5, 0x8800
	v_add3_u32 v236, s1, v186, v152
	v_add3_u32 v178, s2, v152, v154
	v_cvt_f32_u32_e32 v242, s11
	v_add_f32_e32 v242, v185, v242
	v_fma_f32 v239, v242, v250, v169
	v_fma_f32 v253, v242, -v250, v64
	v_sub_f32_e32 v241, v169, v253
	v_mfma_f32_32x32x16_bf16 v[98:113], v[210:213], v[114:117], v[66:81]
	ds_read_b128 v[210:213], v178 offset:23136
	v_sub_f32_e32 v82, v82, v239
	v_sub_f32_e32 v83, v83, v239
	v_sub_f32_e32 v84, v84, v239
	v_sub_f32_e32 v85, v85, v239
	v_exp_f32_e32 v82, v82
	v_mfma_f32_32x32x16_bf16 v[48:63], v[214:217], v[202:205], v[48:63]
	ds_read_b128 v[214:217], v234 offset:8800
	v_exp_f32_e32 v83, v83
	v_exp_f32_e32 v84, v84
	v_exp_f32_e32 v85, v85
	v_mfma_f32_32x32x16_bf16 v[32:47], v[218:221], v[202:205], v[32:47]
	ds_read_b128 v[218:221], v178 offset:27744
	v_add_f32_e32 v191, v191, v82
	v_add_f32_e32 v192, v192, v83
	v_cvt_pk_bf16_f32 v194, v82, v83
	v_add_f32_e32 v191, v191, v84
	v_add_f32_e32 v192, v192, v85
	v_cvt_pk_bf16_f32 v195, v84, v85
	v_mfma_f32_32x32x16_bf16 v[98:113], v[222:225], v[118:121], v[98:113]
	ds_read_b128 v[222:225], v178 offset:32352
	v_sub_f32_e32 v86, v86, v239
	v_sub_f32_e32 v87, v87, v239
	v_sub_f32_e32 v88, v88, v239
	v_sub_f32_e32 v89, v89, v239
	v_exp_f32_e32 v86, v86
	v_mfma_f32_32x32x16_bf16 v[16:31], v[226:229], v[202:205], v[16:31]
	ds_read_b128 v[226:229], v234 offset:17408
	v_exp_f32_e32 v87, v87
	v_exp_f32_e32 v88, v88
	v_exp_f32_e32 v89, v89
	v_mfma_f32_32x32x16_bf16 v[0:15], v[230:233], v[202:205], v[0:15]
	ds_read_b128 v[230:233], v235 offset:0
	v_add_f32_e32 v191, v191, v86
	v_add_f32_e32 v192, v192, v87
	v_cvt_pk_bf16_f32 v196, v86, v87
	v_add_f32_e32 v191, v191, v88
	v_add_f32_e32 v192, v192, v89
	v_cvt_pk_bf16_f32 v197, v88, v89
	v_mfma_f32_32x32x16_bf16 v[98:113], v[174:177], v[122:125], v[98:113]
	ds_read_b128 v[174:177], v235 offset:4608
	v_sub_f32_e32 v90, v90, v239
	v_sub_f32_e32 v91, v91, v239
	v_sub_f32_e32 v92, v92, v239
	v_sub_f32_e32 v93, v93, v239
	v_exp_f32_e32 v90, v90
	v_mfma_f32_32x32x16_bf16 v[48:63], v[246:249], v[206:209], v[48:63]
	ds_read_b128 v[246:249], v234 offset:17440
	v_exp_f32_e32 v91, v91
	v_exp_f32_e32 v92, v92
	v_exp_f32_e32 v93, v93
	s_waitcnt lgkmcnt(7)
	v_mfma_f32_32x32x16_bf16 v[32:47], v[210:213], v[206:209], v[32:47]
	ds_read_b128 v[210:213], v235 offset:9216
	v_add_f32_e32 v191, v191, v90
	v_add_f32_e32 v192, v192, v91
	v_cvt_pk_bf16_f32 v198, v90, v91
	v_add_f32_e32 v191, v191, v92
	v_add_f32_e32 v192, v192, v93
	v_cvt_pk_bf16_f32 v199, v92, v93
	s_waitcnt lgkmcnt(7)
	v_mfma_f32_32x32x16_bf16 v[98:113], v[214:217], v[126:129], v[98:113]
	ds_read_b128 v[214:217], v235 offset:13824
	v_sub_f32_e32 v94, v94, v239
	v_sub_f32_e32 v95, v95, v239
	v_sub_f32_e32 v96, v96, v239
	v_sub_f32_e32 v97, v97, v239
	v_exp_f32_e32 v94, v94
	s_waitcnt lgkmcnt(7)
	v_mfma_f32_32x32x16_bf16 v[16:31], v[218:221], v[206:209], v[16:31]
	ds_read_b128 v[218:221], v234 offset:17472
	v_exp_f32_e32 v95, v95
	v_exp_f32_e32 v96, v96
	v_exp_f32_e32 v97, v97
	s_waitcnt lgkmcnt(7)
	v_mfma_f32_32x32x16_bf16 v[0:15], v[222:225], v[206:209], v[0:15]
	ds_read_b128 v[222:225], v235 offset:32
	v_add_f32_e32 v191, v191, v94
	v_add_f32_e32 v192, v192, v95
	v_cvt_pk_bf16_f32 v200, v94, v95
	v_add_f32_e32 v191, v191, v96
	v_add_f32_e32 v192, v192, v97
	v_cvt_pk_bf16_f32 v201, v96, v97
	s_waitcnt lgkmcnt(0)
	s_barrier
	v_mfma_f32_32x32x16_bf16 v[82:97], v[226:229], v[114:117], v[66:81]
	ds_read_b128 v[226:229], v235 offset:4640
	v_add3_u32 v158, s5, v180, v182
	v_sub_f32_e32 v98, v98, v241
	v_sub_f32_e32 v99, v99, v241
	v_sub_f32_e32 v100, v100, v241
	v_sub_f32_e32 v101, v101, v241
	v_exp_f32_e32 v98, v98
	v_mfma_f32_32x32x16_bf16 v[48:63], v[230:233], v[194:197], v[48:63]
	ds_read_b128 v[230:233], v234 offset:17504
	s_waitcnt vmcnt(3)
	ds_write_b128 v158, v[130:133] offset:0
	s_lshl_b32 s18, s0, 15
	s_mov_b32 s19, 0
	v_lshl_add_u64 v[156:157], v[150:151], 0, s[18:19]
	global_load_dwordx4 v[130:133], v[156:157], off
	v_exp_f32_e32 v99, v99
	v_exp_f32_e32 v100, v100
	v_exp_f32_e32 v101, v101
	v_mfma_f32_32x32x16_bf16 v[32:47], v[174:177], v[194:197], v[32:47]
	ds_read_b128 v[174:177], v235 offset:9248
	v_add_f32_e32 v191, v191, v98
	v_add_f32_e32 v192, v192, v99
	v_cvt_pk_bf16_f32 v202, v98, v99
	v_add_f32_e32 v191, v191, v100
	v_add_f32_e32 v192, v192, v101
	v_cvt_pk_bf16_f32 v203, v100, v101
	v_mfma_f32_32x32x16_bf16 v[82:97], v[246:249], v[118:121], v[82:97]
	ds_read_b128 v[246:249], v235 offset:13856
	s_waitcnt vmcnt(3)
	ds_write_b128 v158, v[134:137] offset:8704
	s_add_u32 s18, s18, 0x2000
	v_lshl_add_u64 v[156:157], v[150:151], 0, s[18:19]
	global_load_dwordx4 v[134:137], v[156:157], off
	v_sub_f32_e32 v102, v102, v241
	v_sub_f32_e32 v103, v103, v241
	v_sub_f32_e32 v104, v104, v241
	v_sub_f32_e32 v105, v105, v241
	v_exp_f32_e32 v102, v102
	v_mfma_f32_32x32x16_bf16 v[16:31], v[210:213], v[194:197], v[16:31]
	ds_read_b128 v[210:213], v234 offset:26112
	v_exp_f32_e32 v103, v103
	v_exp_f32_e32 v104, v104
	v_exp_f32_e32 v105, v105
	v_mfma_f32_32x32x16_bf16 v[0:15], v[214:217], v[194:197], v[0:15]
	ds_read_b128 v[214:217], v235 offset:64
	s_waitcnt vmcnt(3)
; __device__ void da_unit(char* lds, const Params& p, int layer, int unit) {
;     ...
;         DA_FAST_HALF(Bs, -slope2, 0)
;         if (it + 1 < NT) {
; #pragma unroll
;             for (int j = 0; j < 4; ++j) *(u32x4*)(nK + (kr_ + 32 * j) * DA_KP + kc_ * 16) = rk[j];
; #pragma unroll
;             for (int j = 0; j < 4; ++j) rk[j] = *(const u32x4*)(Vg + (size_t)tn * 16384 + j * 4096);
;         }
;         DA_FAST_HALF(Bs, -slope2, 1)
;     ...
;         if (it + 1 < NT) {
; #pragma unroll
;             for (int j = 0; j < 4; ++j) *(u32x4*)(nK + DA_KBYTES + (j >> 1) * DA_VSUB + (vr_ + 64 * (j & 1)) * DA_VP + vc_ * 16) = rk[j];
;         }
	ds_write_b128 v158, v[138:141] offset:17408
	s_add_u32 s18, s18, 0x2000
	v_lshl_add_u64 v[156:157], v[150:151], 0, s[18:19]
	global_load_dwordx4 v[138:141], v[156:157], off
	v_add_f32_e32 v191, v191, v102
	v_add_f32_e32 v192, v192, v103
	v_cvt_pk_bf16_f32 v204, v102, v103
	v_add_f32_e32 v191, v191, v104
	v_add_f32_e32 v192, v192, v105
	v_cvt_pk_bf16_f32 v205, v104, v105
	v_mfma_f32_32x32x16_bf16 v[82:97], v[218:221], v[122:125], v[82:97]
	ds_read_b128 v[218:221], v235 offset:4672
	v_sub_f32_e32 v106, v106, v241
	v_sub_f32_e32 v107, v107, v241
	v_sub_f32_e32 v108, v108, v241
	v_sub_f32_e32 v109, v109, v241
	v_exp_f32_e32 v106, v106
	v_mfma_f32_32x32x16_bf16 v[48:63], v[222:225], v[198:201], v[48:63]
	ds_read_b128 v[222:225], v234 offset:26144
	s_waitcnt vmcnt(3)
	ds_write_b128 v158, v[142:145] offset:26112
	s_add_u32 s18, s18, 0x2000
	v_lshl_add_u64 v[156:157], v[150:151], 0, s[18:19]
	global_load_dwordx4 v[142:145], v[156:157], off
	v_exp_f32_e32 v107, v107
	v_exp_f32_e32 v108, v108
	v_exp_f32_e32 v109, v109
	s_waitcnt lgkmcnt(11)
	v_mfma_f32_32x32x16_bf16 v[32:47], v[226:229], v[198:201], v[32:47]
	ds_read_b128 v[226:229], v235 offset:9280
	v_add_f32_e32 v191, v191, v106
	v_add_f32_e32 v192, v192, v107
	v_cvt_pk_bf16_f32 v206, v106, v107
	v_add_f32_e32 v191, v191, v108
	v_add_f32_e32 v192, v192, v109
	v_cvt_pk_bf16_f32 v207, v108, v109
	s_waitcnt lgkmcnt(11)
	v_mfma_f32_32x32x16_bf16 v[82:97], v[230:233], v[126:129], v[82:97]
	ds_read_b128 v[230:233], v235 offset:13888
	v_sub_f32_e32 v110, v110, v241
	v_sub_f32_e32 v111, v111, v241
	v_sub_f32_e32 v112, v112, v241
	v_sub_f32_e32 v113, v113, v241
	v_exp_f32_e32 v110, v110
	s_waitcnt lgkmcnt(10)
	v_mfma_f32_32x32x16_bf16 v[16:31], v[174:177], v[198:201], v[16:31]
	ds_read_b128 v[174:177], v234 offset:26176
	v_exp_f32_e32 v111, v111
	v_exp_f32_e32 v112, v112
	v_exp_f32_e32 v113, v113
	s_waitcnt lgkmcnt(10)
	v_mfma_f32_32x32x16_bf16 v[0:15], v[246:249], v[198:201], v[0:15]
	ds_read_b128 v[246:249], v235 offset:96
	v_add_f32_e32 v191, v191, v110
	v_add_f32_e32 v192, v192, v111
	v_cvt_pk_bf16_f32 v208, v110, v111
	v_add_f32_e32 v191, v191, v112
	v_add_f32_e32 v192, v192, v113
	v_cvt_pk_bf16_f32 v209, v112, v113
	s_or_b32 s2, s11, 64
	v_cvt_f32_u32_e32 v242, s2
	v_add_f32_e32 v242, v185, v242
	v_fma_f32 v239, v242, v250, v169
	v_fma_f32 v253, v242, -v250, v64
	v_sub_f32_e32 v241, v169, v253
	s_waitcnt lgkmcnt(9)
	v_mfma_f32_32x32x16_bf16 v[98:113], v[210:213], v[114:117], v[66:81]
	ds_read_b128 v[210:213], v235 offset:4704
	v_sub_f32_e32 v82, v82, v239
	v_sub_f32_e32 v83, v83, v239
	v_sub_f32_e32 v84, v84, v239
	v_sub_f32_e32 v85, v85, v239
	v_exp_f32_e32 v82, v82
	s_waitcnt lgkmcnt(9)
	v_mfma_f32_32x32x16_bf16 v[48:63], v[214:217], v[202:205], v[48:63]
	ds_read_b128 v[214:217], v234 offset:26208
	v_exp_f32_e32 v83, v83
	v_exp_f32_e32 v84, v84
	v_exp_f32_e32 v85, v85
	s_waitcnt lgkmcnt(8)
	v_mfma_f32_32x32x16_bf16 v[32:47], v[218:221], v[202:205], v[32:47]
	ds_read_b128 v[218:221], v235 offset:9312
	v_add_f32_e32 v191, v191, v82
	v_add_f32_e32 v192, v192, v83
	v_cvt_pk_bf16_f32 v194, v82, v83
	v_add_f32_e32 v191, v191, v84
	v_add_f32_e32 v192, v192, v85
	v_cvt_pk_bf16_f32 v195, v84, v85
	s_waitcnt lgkmcnt(8)
	v_mfma_f32_32x32x16_bf16 v[98:113], v[222:225], v[118:121], v[98:113]
	ds_read_b128 v[222:225], v235 offset:13920
	v_sub_f32_e32 v86, v86, v239
	v_sub_f32_e32 v87, v87, v239
	v_sub_f32_e32 v88, v88, v239
	v_sub_f32_e32 v89, v89, v239
	v_exp_f32_e32 v86, v86
	s_waitcnt lgkmcnt(7)
	v_mfma_f32_32x32x16_bf16 v[16:31], v[226:229], v[202:205], v[16:31]
	ds_read_b128 v[226:229], v235 offset:18432
	v_exp_f32_e32 v87, v87
	v_exp_f32_e32 v88, v88
	v_exp_f32_e32 v89, v89
	s_waitcnt lgkmcnt(7)
	v_mfma_f32_32x32x16_bf16 v[0:15], v[230:233], v[202:205], v[0:15]
	ds_read_b128 v[230:233], v235 offset:23040
	v_add3_u32 v158, s5, v183, v181
	v_add_f32_e32 v191, v191, v86
	v_add_f32_e32 v192, v192, v87
	v_cvt_pk_bf16_f32 v196, v86, v87
	v_add_f32_e32 v191, v191, v88
	v_add_f32_e32 v192, v192, v89
	v_cvt_pk_bf16_f32 v197, v88, v89
	s_waitcnt lgkmcnt(7)
	v_mfma_f32_32x32x16_bf16 v[98:113], v[174:177], v[122:125], v[98:113]
	s_waitcnt vmcnt(3)
	ds_write_b128 v158, v[130:133] offset:34816
	v_sub_f32_e32 v90, v90, v239
	v_sub_f32_e32 v91, v91, v239
	v_sub_f32_e32 v92, v92, v239
	v_sub_f32_e32 v93, v93, v239
	v_exp_f32_e32 v90, v90
	s_waitcnt lgkmcnt(7)
	v_mfma_f32_32x32x16_bf16 v[48:63], v[246:249], v[206:209], v[48:63]
	ds_read_b128 v[246:249], v235 offset:27648
	s_waitcnt vmcnt(2)
	ds_write_b128 v158, v[134:137] offset:44032
	v_exp_f32_e32 v91, v91
	v_exp_f32_e32 v92, v92
	v_exp_f32_e32 v93, v93
	s_waitcnt lgkmcnt(8)
	v_mfma_f32_32x32x16_bf16 v[32:47], v[210:213], v[206:209], v[32:47]
	ds_read_b128 v[210:213], v235 offset:32256
	s_waitcnt vmcnt(1)
	ds_write_b128 v158, v[138:141] offset:53248
	v_add_f32_e32 v191, v191, v90
	v_add_f32_e32 v192, v192, v91
	v_cvt_pk_bf16_f32 v198, v90, v91
	v_add_f32_e32 v191, v191, v92
	v_add_f32_e32 v192, v192, v93
	v_cvt_pk_bf16_f32 v199, v92, v93
	s_waitcnt lgkmcnt(9)
	v_mfma_f32_32x32x16_bf16 v[98:113], v[214:217], v[126:129], v[98:113]
	s_waitcnt vmcnt(0)
	ds_write_b128 v158, v[142:145] offset:62464
	v_sub_f32_e32 v94, v94, v239
	v_sub_f32_e32 v95, v95, v239
	v_sub_f32_e32 v96, v96, v239
	v_sub_f32_e32 v97, v97, v239
	v_exp_f32_e32 v94, v94
	s_waitcnt lgkmcnt(9)
	v_mfma_f32_32x32x16_bf16 v[16:31], v[218:221], v[206:209], v[16:31]
	ds_read_b128 v[218:221], v235 offset:18464
	v_exp_f32_e32 v95, v95
	v_exp_f32_e32 v96, v96
	v_exp_f32_e32 v97, v97
	s_waitcnt lgkmcnt(9)
	v_mfma_f32_32x32x16_bf16 v[0:15], v[222:225], v[206:209], v[0:15]
	ds_read_b128 v[222:225], v235 offset:23072
	v_add_f32_e32 v191, v191, v94
	v_add_f32_e32 v192, v192, v95
	v_cvt_pk_bf16_f32 v200, v94, v95
	v_add_f32_e32 v191, v191, v96
	v_add_f32_e32 v192, v192, v97
	v_cvt_pk_bf16_f32 v201, v96, v97
	s_waitcnt lgkmcnt(0)
	s_barrier
	s_cmp_lt_u32 s4, 14
	s_cbranch_scc0 .Lda_nok
	s_lshl_b32 s18, s3, 15
	s_mov_b32 s19, 0
	v_lshl_add_u64 v[156:157], v[148:149], 0, s[18:19]
	global_load_dwordx4 v[130:133], v[156:157], off
	s_add_u32 s18, s18, 0x2000
	v_lshl_add_u64 v[156:157], v[148:149], 0, s[18:19]
	global_load_dwordx4 v[134:137], v[156:157], off
	s_add_u32 s18, s18, 0x2000
	v_lshl_add_u64 v[156:157], v[148:149], 0, s[18:19]
	global_load_dwordx4 v[138:141], v[156:157], off
	s_add_u32 s18, s18, 0x2000
	v_lshl_add_u64 v[156:157], v[148:149], 0, s[18:19]
	global_load_dwordx4 v[142:145], v[156:157], off

.Lda_nocflip:
	ds_read_b128 v[174:177], v236 offset:0
	ds_read_b128 v[214:217], v236 offset:32
	v_mfma_f32_32x32x16_bf16 v[48:63], v[226:229], v[194:197], v[48:63]
	ds_read_b128 v[226:229], v236 offset:64
	v_sub_f32_e32 v98, v98, v241
	v_sub_f32_e32 v99, v99, v241
	v_sub_f32_e32 v100, v100, v241
	v_sub_f32_e32 v101, v101, v241
	v_exp_f32_e32 v98, v98
	v_mfma_f32_32x32x16_bf16 v[32:47], v[230:233], v[194:197], v[32:47]
	ds_read_b128 v[230:233], v235 offset:27680
	v_exp_f32_e32 v99, v99
	v_exp_f32_e32 v100, v100
	v_exp_f32_e32 v101, v101
	s_waitcnt lgkmcnt(3)
	v_mfma_f32_32x32x16_bf16 v[82:97], v[174:177], v[114:117], v[66:81]
	ds_read_b128 v[174:177], v235 offset:32288
	v_add_f32_e32 v191, v191, v98
	v_add_f32_e32 v192, v192, v99
	v_cvt_pk_bf16_f32 v202, v98, v99
	v_add_f32_e32 v191, v191, v100
	v_add_f32_e32 v192, v192, v101
	v_cvt_pk_bf16_f32 v203, v100, v101
	v_mfma_f32_32x32x16_bf16 v[16:31], v[246:249], v[194:197], v[16:31]
	ds_read_b128 v[246:249], v236 offset:96
	v_sub_f32_e32 v102, v102, v241
	v_sub_f32_e32 v103, v103, v241
	v_sub_f32_e32 v104, v104, v241
	v_sub_f32_e32 v105, v105, v241
	v_exp_f32_e32 v102, v102
	v_mfma_f32_32x32x16_bf16 v[0:15], v[210:213], v[194:197], v[0:15]
	ds_read_b128 v[210:213], v236 offset:8704
	v_exp_f32_e32 v103, v103
	v_exp_f32_e32 v104, v104
	v_exp_f32_e32 v105, v105
	s_waitcnt lgkmcnt(5)
	v_mfma_f32_32x32x16_bf16 v[82:97], v[214:217], v[118:121], v[82:97]
	ds_read_b128 v[214:217], v235 offset:18496
	v_add_f32_e32 v191, v191, v102
	v_add_f32_e32 v192, v192, v103
	v_cvt_pk_bf16_f32 v204, v102, v103
	v_add_f32_e32 v191, v191, v104
	v_add_f32_e32 v192, v192, v105
	v_cvt_pk_bf16_f32 v205, v104, v105
	v_mfma_f32_32x32x16_bf16 v[48:63], v[218:221], v[198:201], v[48:63]
	ds_read_b128 v[218:221], v235 offset:23104
	v_sub_f32_e32 v106, v106, v241
	v_sub_f32_e32 v107, v107, v241
	v_sub_f32_e32 v108, v108, v241
	v_sub_f32_e32 v109, v109, v241
	v_exp_f32_e32 v106, v106
	v_mfma_f32_32x32x16_bf16 v[32:47], v[222:225], v[198:201], v[32:47]
	ds_read_b128 v[222:225], v236 offset:8736
	v_exp_f32_e32 v107, v107
	v_exp_f32_e32 v108, v108
	v_exp_f32_e32 v109, v109
	s_waitcnt lgkmcnt(7)
	v_mfma_f32_32x32x16_bf16 v[82:97], v[226:229], v[122:125], v[82:97]
	ds_read_b128 v[226:229], v235 offset:27712
	v_add_f32_e32 v191, v191, v106
	v_add_f32_e32 v192, v192, v107
	v_cvt_pk_bf16_f32 v206, v106, v107
	v_add_f32_e32 v191, v191, v108
	v_add_f32_e32 v192, v192, v109
	v_cvt_pk_bf16_f32 v207, v108, v109
	s_waitcnt lgkmcnt(7)
	v_mfma_f32_32x32x16_bf16 v[16:31], v[230:233], v[198:201], v[16:31]
	ds_read_b128 v[230:233], v235 offset:32320
	v_sub_f32_e32 v110, v110, v241
	v_sub_f32_e32 v111, v111, v241
	v_sub_f32_e32 v112, v112, v241
	v_sub_f32_e32 v113, v113, v241
	v_exp_f32_e32 v110, v110
	s_waitcnt lgkmcnt(7)
	v_mfma_f32_32x32x16_bf16 v[0:15], v[174:177], v[198:201], v[0:15]
	ds_read_b128 v[174:177], v236 offset:8768
	v_exp_f32_e32 v111, v111
	v_exp_f32_e32 v112, v112
	v_exp_f32_e32 v113, v113
	s_waitcnt lgkmcnt(7)
	v_mfma_f32_32x32x16_bf16 v[82:97], v[246:249], v[126:129], v[82:97]
	ds_read_b128 v[246:249], v235 offset:18528
	v_add_f32_e32 v191, v191, v110
	v_add_f32_e32 v192, v192, v111
	v_cvt_pk_bf16_f32 v208, v110, v111
	v_add_f32_e32 v191, v191, v112
	v_add_f32_e32 v192, v192, v113
	v_cvt_pk_bf16_f32 v209, v112, v113
	s_add_i32 s4, s4, 1
	s_cmp_lt_u32 s4, 16
	s_waitcnt lgkmcnt(0)
	s_cbranch_scc1 .Lda_top
	ds_read_b128 v[210:213], v235 offset:23136
	ds_read_b128 v[222:225], v235 offset:32352
	v_mfma_f32_32x32x16_bf16 v[48:63], v[214:217], v[202:205], v[48:63]
	v_mfma_f32_32x32x16_bf16 v[32:47], v[218:221], v[202:205], v[32:47]
	ds_read_b128 v[218:221], v235 offset:27744
	v_mfma_f32_32x32x16_bf16 v[16:31], v[226:229], v[202:205], v[16:31]
	v_mfma_f32_32x32x16_bf16 v[0:15], v[230:233], v[202:205], v[0:15]
	v_mfma_f32_32x32x16_bf16 v[48:63], v[246:249], v[206:209], v[48:63]
	s_waitcnt lgkmcnt(2)
	v_mfma_f32_32x32x16_bf16 v[32:47], v[210:213], v[206:209], v[32:47]
	s_waitcnt lgkmcnt(0)
	v_mfma_f32_32x32x16_bf16 v[16:31], v[218:221], v[206:209], v[16:31]
	v_mfma_f32_32x32x16_bf16 v[0:15], v[222:225], v[206:209], v[0:15]
	v_add_f32_e32 v191, v191, v192
	s_nop 7
	s_nop 3
	v_add_f32_e32 v193, v193, v191
